# NSA sliding-window loop: same hand-scheduled interleaved fast path for unmasked tiles as the selected-branch loop
# speedup vs baseline: 1.0035x; 1.0027x over previous
.Lwin_end:
	s_waitcnt vmcnt(0) lgkmcnt(0)
	s_barrier
	s_cmp_lg_u32 s73, s76
	s_cbranch_scc0 .LBB0_773

.LBB0_769:
	s_add_i32 s77, s77, 0
	s_cmp_eq_u32 s73, s76
	s_cbranch_scc0 .Lwin_fast
	v_add_u32_e32 v0, s77, v184
	ds_read_b128 v[66:69], v0
	ds_read_b128 v[86:89], v0 offset:8192
	v_add_u32_e32 v0, s77, v185
	ds_read_b128 v[156:159], v0
	ds_read_b128 v[194:197], v0 offset:8192
	v_add_u32_e32 v0, s77, v186
	ds_read_b128 v[198:201], v0
	ds_read_b128 v[202:205], v0 offset:8192
	s_waitcnt lgkmcnt(0)
	v_mfma_f32_32x32x16_bf16 v[70:85], v[66:69], v[140:143], 0
	v_mfma_f32_32x32x16_bf16 v[86:101], v[86:89], v[140:143], 0
	v_add_u32_e32 v0, s77, v183
	ds_read_b128 v[66:69], v0
	ds_read_b128 v[206:209], v0 offset:8192
	v_mfma_f32_32x32x16_bf16 v[70:85], v[156:159], v[136:139], v[70:85]
	v_mfma_f32_32x32x16_bf16 v[86:101], v[194:197], v[136:139], v[86:101]
	v_add_u32_e32 v0, s77, v182
	ds_read_b128 v[156:159], v0
	ds_read_b128 v[194:197], v0 offset:8192
	v_mfma_f32_32x32x16_bf16 v[70:85], v[198:201], v[132:135], v[70:85]
	v_mfma_f32_32x32x16_bf16 v[86:101], v[202:205], v[132:135], v[86:101]
	v_add_u32_e32 v0, s77, v181
	ds_read_b128 v[198:201], v0
	ds_read_b128 v[202:205], v0 offset:8192
	s_waitcnt lgkmcnt(0)
	v_mfma_f32_32x32x16_bf16 v[70:85], v[66:69], v[128:131], v[70:85]
	v_mfma_f32_32x32x16_bf16 v[86:101], v[206:209], v[128:131], v[86:101]
	v_add_u32_e32 v0, s77, v180
	ds_read_b128 v[66:69], v0
	ds_read_b128 v[206:209], v0 offset:8192
	v_mfma_f32_32x32x16_bf16 v[70:85], v[156:159], v[124:127], v[70:85]
	v_mfma_f32_32x32x16_bf16 v[86:101], v[194:197], v[124:127], v[86:101]
	v_add_u32_e32 v0, s77, v179
	ds_read_b128 v[156:159], v0
	ds_read_b128 v[194:197], v0 offset:8192
	v_mfma_f32_32x32x16_bf16 v[70:85], v[198:201], v[120:123], v[70:85]
	v_mfma_f32_32x32x16_bf16 v[86:101], v[202:205], v[120:123], v[86:101]
	s_waitcnt lgkmcnt(0)
	v_mfma_f32_32x32x16_bf16 v[70:85], v[66:69], v[116:119], v[70:85]
	v_mfma_f32_32x32x16_bf16 v[86:101], v[206:209], v[116:119], v[86:101]
	v_mfma_f32_32x32x16_bf16 v[70:85], v[156:159], v[112:115], v[70:85]
	v_mfma_f32_32x32x16_bf16 v[86:101], v[194:197], v[112:115], v[86:101]
	s_nop 10
	v_exp_f32_e32 v68, v70
	v_exp_f32_e32 v0, v86
	v_exp_f32_e32 v71, v71
	v_exp_f32_e32 v67, v87
	v_exp_f32_e32 v70, v72
	v_exp_f32_e32 v66, v88
	v_exp_f32_e32 v73, v73
	v_exp_f32_e32 v69, v89
	v_exp_f32_e32 v88, v74
	v_exp_f32_e32 v74, v90
	v_exp_f32_e32 v89, v75
	v_exp_f32_e32 v75, v91
	v_exp_f32_e32 v106, v76
	v_exp_f32_e32 v86, v92
	v_exp_f32_e32 v107, v77
	v_exp_f32_e32 v87, v93
	v_exp_f32_e32 v90, v78
	v_exp_f32_e32 v76, v94
	v_exp_f32_e32 v91, v79
	v_exp_f32_e32 v77, v95
	v_exp_f32_e32 v92, v80
	v_exp_f32_e32 v78, v96
	v_exp_f32_e32 v93, v81
	v_exp_f32_e32 v79, v97
	v_exp_f32_e32 v94, v82
	v_exp_f32_e32 v80, v98
	v_exp_f32_e32 v95, v83
	v_exp_f32_e32 v81, v99
	v_exp_f32_e32 v84, v84
	v_exp_f32_e32 v82, v100
	v_exp_f32_e32 v85, v85
	v_exp_f32_e32 v83, v101
	s_cmp_eq_u32 s73, s76
	s_mov_b64 s[2:3], -1
	s_cbranch_scc1 .LBB0_771
	s_mov_b64 s[2:3], 0

.Lwin_fast:
	v_add_u32_e32 v0, s77, v184
	ds_read_b128 v[66:69], v0
	v_add_u32_e32 v0, s77, v185
	ds_read_b128 v[156:159], v0
	v_add_u32_e32 v0, s77, v186
	ds_read_b128 v[194:197], v0
	v_add_u32_e32 v0, s77, v183
	ds_read_b128 v[198:201], v0
	s_waitcnt lgkmcnt(3)
	v_mfma_f32_32x32x16_bf16 v[70:85], v[66:69], v[140:143], 0
	v_add_u32_e32 v218, s77, v153
	v_add3_u32 v210, v218, v109, v178
	v_add_u32_e32 v0, s77, v182
	ds_read_b128 v[66:69], v0
	s_waitcnt lgkmcnt(3)
	v_mfma_f32_32x32x16_bf16 v[70:85], v[156:159], v[136:139], v[70:85]
	v_add_u32_e32 v211, s77, v110
	v_add3_u32 v211, v211, v178, v153
	v_add_u32_e32 v0, s77, v181
	ds_read_b128 v[156:159], v0
	s_waitcnt lgkmcnt(3)
	v_mfma_f32_32x32x16_bf16 v[70:85], v[194:197], v[132:135], v[70:85]
	v_add3_u32 v212, v218, v111, v178
	v_add_u32_e32 v213, s77, v144
	v_add_u32_e32 v0, s77, v180
	ds_read_b128 v[194:197], v0
	s_waitcnt lgkmcnt(3)
	v_mfma_f32_32x32x16_bf16 v[70:85], v[198:201], v[128:131], v[70:85]
	v_add3_u32 v213, v213, v178, v153
	v_add3_u32 v214, v218, v145, v178
	v_add_u32_e32 v0, s77, v179
	ds_read_b128 v[198:201], v0
	s_waitcnt lgkmcnt(3)
	v_mfma_f32_32x32x16_bf16 v[70:85], v[66:69], v[124:127], v[70:85]
	v_add_u32_e32 v215, s77, v146
	v_add3_u32 v215, v215, v178, v153
	v_add_u32_e32 v0, s77, v184
	ds_read_b128 v[66:69], v0 offset:8192
	s_waitcnt lgkmcnt(3)
	v_mfma_f32_32x32x16_bf16 v[70:85], v[156:159], v[120:123], v[70:85]
	v_add3_u32 v216, v218, v147, v178
	v_add_u32_e32 v217, s77, v149
	v_add_u32_e32 v0, s77, v185
	ds_read_b128 v[156:159], v0 offset:8192
	s_waitcnt lgkmcnt(3)
	v_mfma_f32_32x32x16_bf16 v[70:85], v[194:197], v[116:119], v[70:85]
	v_add3_u32 v217, v217, v178, v153
	v_add_u32_e32 v0, s77, v186
	ds_read_b128 v[194:197], v0 offset:8192
	s_waitcnt lgkmcnt(3)
	v_mfma_f32_32x32x16_bf16 v[70:85], v[198:201], v[112:115], v[70:85]
	v_add_u32_e32 v0, s77, v183
	ds_read_b128 v[198:201], v0 offset:8192
	s_waitcnt lgkmcnt(3)
	v_mfma_f32_32x32x16_bf16 v[86:101], v[66:69], v[140:143], 0
	v_add_u32_e32 v0, s77, v182
	ds_read_b128 v[66:69], v0 offset:8192
	s_waitcnt lgkmcnt(3)
	v_mfma_f32_32x32x16_bf16 v[86:101], v[156:159], v[136:139], v[86:101]
	v_add_u32_e32 v0, s77, v181
	ds_read_b128 v[156:159], v0 offset:8192
	s_waitcnt lgkmcnt(3)
	v_mfma_f32_32x32x16_bf16 v[86:101], v[194:197], v[132:135], v[86:101]
	v_add_u32_e32 v0, s77, v180
	ds_read_b128 v[194:197], v0 offset:8192
	s_waitcnt lgkmcnt(3)
	v_mfma_f32_32x32x16_bf16 v[86:101], v[198:201], v[128:131], v[86:101]
	v_add_u32_e32 v0, s77, v179
	ds_read_b128 v[198:201], v0 offset:8192
	v_exp_f32_e32 v70, v70
	v_exp_f32_e32 v71, v71
	v_exp_f32_e32 v72, v72
	s_waitcnt lgkmcnt(3)
	v_mfma_f32_32x32x16_bf16 v[86:101], v[66:69], v[124:127], v[86:101]
	v_exp_f32_e32 v73, v73
	v_exp_f32_e32 v74, v74
	v_exp_f32_e32 v75, v75
	s_waitcnt lgkmcnt(2)
	v_mfma_f32_32x32x16_bf16 v[86:101], v[156:159], v[120:123], v[86:101]
	v_exp_f32_e32 v76, v76
	v_exp_f32_e32 v77, v77
	v_exp_f32_e32 v78, v78
	s_waitcnt lgkmcnt(1)
	v_mfma_f32_32x32x16_bf16 v[86:101], v[194:197], v[116:119], v[86:101]
	v_exp_f32_e32 v79, v79
	v_exp_f32_e32 v80, v80
	v_exp_f32_e32 v81, v81
	s_waitcnt lgkmcnt(0)
	v_mfma_f32_32x32x16_bf16 v[86:101], v[198:201], v[112:115], v[86:101]
	v_exp_f32_e32 v82, v82
	v_exp_f32_e32 v83, v83
	v_exp_f32_e32 v84, v84
	v_exp_f32_e32 v85, v85
	ds_read_b64_tr_b16 v[220:221], v210 offset:32768
	ds_read_b64_tr_b16 v[222:223], v211 offset:34816
	ds_read_b64_tr_b16 v[224:225], v210 offset:36864
	ds_read_b64_tr_b16 v[226:227], v211 offset:38912
	ds_read_b64_tr_b16 v[228:229], v212 offset:32768
	ds_read_b64_tr_b16 v[230:231], v213 offset:34816
	ds_read_b64_tr_b16 v[232:233], v212 offset:36864
	ds_read_b64_tr_b16 v[234:235], v213 offset:38912
	s_nop 0
	v_pk_add_f32 v[244:245], v[70:71], v[72:73]
	v_pk_add_f32 v[246:247], v[74:75], v[76:77]
	v_pk_add_f32 v[156:157], v[78:79], v[80:81]
	v_pk_add_f32 v[158:159], v[82:83], v[84:85]
	v_pk_add_f32 v[244:245], v[244:245], v[246:247]
	v_pk_add_f32 v[156:157], v[156:157], v[158:159]
	v_pk_add_f32 v[244:245], v[244:245], v[156:157]
	v_add_f32_e32 v219, v244, v245
	v_cvt_pk_bf16_f32 v202, v70, v71
	v_cvt_pk_bf16_f32 v203, v72, v73
	v_cvt_pk_bf16_f32 v204, v74, v75
	v_cvt_pk_bf16_f32 v205, v76, v77
	v_cvt_pk_bf16_f32 v78, v78, v79
	v_cvt_pk_bf16_f32 v79, v80, v81
	v_cvt_pk_bf16_f32 v80, v82, v83
	v_cvt_pk_bf16_f32 v81, v84, v85
	ds_read_b64_tr_b16 v[70:71], v214 offset:32768
	ds_read_b64_tr_b16 v[72:73], v215 offset:34816
	ds_read_b64_tr_b16 v[74:75], v214 offset:36864
	ds_read_b64_tr_b16 v[76:77], v215 offset:38912
	ds_read_b64_tr_b16 v[82:83], v216 offset:32768
	ds_read_b64_tr_b16 v[84:85], v217 offset:34816
	ds_read_b64_tr_b16 v[236:237], v216 offset:36864
	ds_read_b64_tr_b16 v[238:239], v217 offset:38912
	s_waitcnt lgkmcnt(8)
	v_mfma_f32_32x32x16_bf16 v[2:17], v[202:205], v[220:223], v[2:17]
	v_exp_f32_e32 v86, v86
	v_exp_f32_e32 v87, v87
	v_mfma_f32_32x32x16_bf16 v[2:17], v[78:81], v[224:227], v[2:17]
	v_exp_f32_e32 v88, v88
	v_exp_f32_e32 v89, v89
	ds_read_b64_tr_b16 v[220:221], v210 offset:40960
	ds_read_b64_tr_b16 v[222:223], v211 offset:43008
	ds_read_b64_tr_b16 v[224:225], v210 offset:45056
	ds_read_b64_tr_b16 v[226:227], v211 offset:47104
	v_mfma_f32_32x32x16_bf16 v[18:33], v[202:205], v[228:231], v[18:33]
	v_exp_f32_e32 v90, v90
	v_exp_f32_e32 v91, v91
	v_mfma_f32_32x32x16_bf16 v[18:33], v[78:81], v[232:235], v[18:33]
	v_exp_f32_e32 v92, v92
	v_exp_f32_e32 v93, v93
	ds_read_b64_tr_b16 v[228:229], v212 offset:40960
	ds_read_b64_tr_b16 v[230:231], v213 offset:43008
	ds_read_b64_tr_b16 v[232:233], v212 offset:45056
	ds_read_b64_tr_b16 v[234:235], v213 offset:47104
	s_waitcnt lgkmcnt(8)
	v_mfma_f32_32x32x16_bf16 v[34:49], v[202:205], v[70:73], v[34:49]
	v_exp_f32_e32 v94, v94
	v_exp_f32_e32 v95, v95
	v_cvt_pk_bf16_f32 v206, v86, v87
	v_cvt_pk_bf16_f32 v207, v88, v89
	v_mfma_f32_32x32x16_bf16 v[34:49], v[78:81], v[74:77], v[34:49]
	v_exp_f32_e32 v96, v96
	v_exp_f32_e32 v97, v97
	v_cvt_pk_bf16_f32 v208, v90, v91
	v_cvt_pk_bf16_f32 v209, v92, v93
	ds_read_b64_tr_b16 v[70:71], v214 offset:40960
	ds_read_b64_tr_b16 v[72:73], v215 offset:43008
	ds_read_b64_tr_b16 v[74:75], v214 offset:45056
	ds_read_b64_tr_b16 v[76:77], v215 offset:47104
	v_mfma_f32_32x32x16_bf16 v[50:65], v[202:205], v[82:85], v[50:65]
	v_exp_f32_e32 v98, v98
	v_exp_f32_e32 v99, v99
	v_mfma_f32_32x32x16_bf16 v[50:65], v[78:81], v[236:239], v[50:65]
	v_exp_f32_e32 v100, v100
	v_exp_f32_e32 v101, v101
	ds_read_b64_tr_b16 v[82:83], v216 offset:40960
	ds_read_b64_tr_b16 v[84:85], v217 offset:43008
	ds_read_b64_tr_b16 v[236:237], v216 offset:45056
	ds_read_b64_tr_b16 v[238:239], v217 offset:47104
	s_add_i32 s76, s76, 1
	s_waitcnt lgkmcnt(14)
	v_mfma_f32_32x32x16_bf16 v[2:17], v[206:209], v[220:223], v[2:17]
	v_pk_add_f32 v[244:245], v[86:87], v[88:89]
	v_pk_add_f32 v[246:247], v[90:91], v[92:93]
	v_pk_add_f32 v[156:157], v[94:95], v[96:97]
	v_pk_add_f32 v[158:159], v[98:99], v[100:101]
	s_waitcnt lgkmcnt(10)
	v_mfma_f32_32x32x16_bf16 v[18:33], v[206:209], v[228:231], v[18:33]
	v_pk_add_f32 v[244:245], v[244:245], v[246:247]
	v_pk_add_f32 v[156:157], v[156:157], v[158:159]
	v_pk_add_f32 v[244:245], v[244:245], v[156:157]
	v_add_f32_e32 v244, v244, v245
	s_waitcnt lgkmcnt(6)
	v_mfma_f32_32x32x16_bf16 v[34:49], v[206:209], v[70:73], v[34:49]
	v_cvt_pk_bf16_f32 v240, v94, v95
	v_cvt_pk_bf16_f32 v241, v96, v97
	v_cvt_pk_bf16_f32 v242, v98, v99
	v_cvt_pk_bf16_f32 v243, v100, v101
	s_waitcnt lgkmcnt(2)
	v_mfma_f32_32x32x16_bf16 v[50:65], v[206:209], v[82:85], v[50:65]
	v_add_f32_e32 v219, v219, v244
	v_add_f32_e32 v108, v108, v219
	s_nop 1
	s_waitcnt lgkmcnt(0)
	v_mfma_f32_32x32x16_bf16 v[2:17], v[240:243], v[224:227], v[2:17]
	v_mfma_f32_32x32x16_bf16 v[18:33], v[240:243], v[232:235], v[18:33]
	v_mfma_f32_32x32x16_bf16 v[34:49], v[240:243], v[74:77], v[34:49]
	v_mfma_f32_32x32x16_bf16 v[50:65], v[240:243], v[236:239], v[50:65]
	s_branch .Lwin_end
